# scan-phase weight conversion: 8 k-scale loads batched (were 8 serialized round trips), nt on its once-read f32 loads
# speedup vs baseline: 1.0089x; 1.0089x over previous
.LBB0_863:
	s_ashr_i32 s64, s66, 31
	s_lshr_b32 s64, s64, 27
	s_add_i32 s64, s66, s64
	s_and_b32 s65, s64, 0xffffffe0
	s_lshl_b32 s64, s64, 1
	s_andn2_b32 s64, s64, 63
	s_sub_i32 vcc_lo, s66, s65
	s_waitcnt vmcnt(3)
	v_or_b32_e32 v52, s64, v144
	s_ashr_i32 s65, s64, 31
	s_mul_i32 s67, s65, s54
	v_mad_u64_u32 v[52:53], s[78:79], v52, s54, 0
	s_lshl_b32 s66, vcc_lo, 6
	v_add_u32_e32 v53, s67, v53
	s_waitcnt lgkmcnt(0)
	v_lshl_add_u64 v[52:53], v[52:53], 2, s[70:71]
	s_ashr_i32 s67, s66, 31
	v_lshl_add_u64 v[52:53], s[66:67], 2, v[52:53]
	v_lshl_add_u64 v[52:53], v[52:53], 0, v[118:119]
	v_lshl_add_u64 v[54:55], s[54:55], 2, v[52:53]
	s_lshl_b32 s70, s54, 3
	s_mov_b32 s71, s55
	global_load_dwordx4 v[108:111], v[52:53], off nt
	global_load_dwordx4 v[112:115], v[54:55], off nt
	v_lshl_add_u64 v[54:55], s[70:71], 2, v[52:53]
	s_mul_i32 s70, s54, 9
	s_waitcnt vmcnt(4)
	v_lshl_add_u64 v[56:57], s[70:71], 2, v[52:53]
	s_lshl_b32 s70, s54, 4
	global_load_dwordx4 v[100:103], v[54:55], off nt
	global_load_dwordx4 v[104:107], v[56:57], off nt
	v_lshl_add_u64 v[54:55], s[70:71], 2, v[52:53]
	s_mul_i32 s70, s54, 17
	v_lshl_add_u64 v[56:57], s[70:71], 2, v[52:53]
	s_mul_i32 s70, s54, 24
	global_load_dwordx4 v[92:95], v[54:55], off nt
	global_load_dwordx4 v[96:99], v[56:57], off nt
	v_lshl_add_u64 v[54:55], s[70:71], 2, v[52:53]
	s_mul_i32 s70, s54, 25
	v_lshl_add_u64 v[56:57], s[70:71], 2, v[52:53]
	s_lshl_b32 s70, s54, 5
	global_load_dwordx4 v[84:87], v[54:55], off nt
	global_load_dwordx4 v[88:91], v[56:57], off nt
	v_lshl_add_u64 v[54:55], s[70:71], 2, v[52:53]
	s_mul_i32 s70, s54, 33
	v_lshl_add_u64 v[56:57], s[70:71], 2, v[52:53]
	s_mul_i32 s70, s54, 40
	global_load_dwordx4 v[76:79], v[54:55], off nt
	global_load_dwordx4 v[80:83], v[56:57], off nt
	v_lshl_add_u64 v[54:55], s[70:71], 2, v[52:53]
	s_mul_i32 s70, s54, 41
	v_lshl_add_u64 v[56:57], s[70:71], 2, v[52:53]
	s_mul_i32 s70, s54, 48
	global_load_dwordx4 v[68:71], v[54:55], off nt
	global_load_dwordx4 v[72:75], v[56:57], off nt
	v_lshl_add_u64 v[54:55], s[70:71], 2, v[52:53]
	s_mul_i32 s70, s54, 49
	v_lshl_add_u64 v[56:57], s[70:71], 2, v[52:53]
	s_mul_i32 s70, s54, 56
	s_mul_i32 s54, s54, 57
	global_load_dwordx4 v[60:63], v[54:55], off nt
	global_load_dwordx4 v[64:67], v[56:57], off nt
	v_lshl_add_u64 v[54:55], s[70:71], 2, v[52:53]
	v_lshl_add_u64 v[56:57], s[54:55], 2, v[52:53]
	global_load_dwordx4 v[52:55], v[54:55], off nt
	s_nop 0
	global_load_dwordx4 v[56:59], v[56:57], off nt
	s_cmp_eq_u64 s[68:69], 0
	s_cbranch_scc1 .LBB0_852
	v_or_b32_e32 v170, s64, v145
	v_ashrrev_i32_e32 v171, 31, v170
	v_lshl_add_u64 v[170:171], v[170:171], 2, s[68:69]
	global_load_dwordx2 v[184:185], v[170:171], off
	global_load_dwordx2 v[186:187], v[170:171], off offset:32
	global_load_dwordx2 v[188:189], v[170:171], off offset:64
	global_load_dwordx2 v[190:191], v[170:171], off offset:96
	global_load_dwordx2 v[192:193], v[170:171], off offset:128
	global_load_dwordx2 v[194:195], v[170:171], off offset:160
	global_load_dwordx2 v[196:197], v[170:171], off offset:192
	global_load_dwordx2 v[198:199], v[170:171], off offset:224
	s_waitcnt vmcnt(7)
	v_pk_mul_f32 v[110:111], v[110:111], v[184:185] op_sel_hi:[1,0]
	v_pk_mul_f32 v[108:109], v[108:109], v[184:185] op_sel_hi:[1,0]
	v_pk_mul_f32 v[114:115], v[114:115], v[184:185] op_sel:[0,1]
	v_pk_mul_f32 v[112:113], v[112:113], v[184:185] op_sel:[0,1]
	s_waitcnt vmcnt(6)
	v_pk_mul_f32 v[102:103], v[102:103], v[186:187] op_sel_hi:[1,0]
	v_pk_mul_f32 v[100:101], v[100:101], v[186:187] op_sel_hi:[1,0]
	v_pk_mul_f32 v[106:107], v[106:107], v[186:187] op_sel:[0,1]
	v_pk_mul_f32 v[104:105], v[104:105], v[186:187] op_sel:[0,1]
	s_waitcnt vmcnt(5)
	v_pk_mul_f32 v[94:95], v[94:95], v[188:189] op_sel_hi:[1,0]
	v_pk_mul_f32 v[92:93], v[92:93], v[188:189] op_sel_hi:[1,0]
	v_pk_mul_f32 v[98:99], v[98:99], v[188:189] op_sel:[0,1]
	v_pk_mul_f32 v[96:97], v[96:97], v[188:189] op_sel:[0,1]
	s_waitcnt vmcnt(4)
	v_pk_mul_f32 v[86:87], v[86:87], v[190:191] op_sel_hi:[1,0]
	v_pk_mul_f32 v[84:85], v[84:85], v[190:191] op_sel_hi:[1,0]
	v_pk_mul_f32 v[90:91], v[90:91], v[190:191] op_sel:[0,1]
	v_pk_mul_f32 v[88:89], v[88:89], v[190:191] op_sel:[0,1]
	s_waitcnt vmcnt(3)
	v_pk_mul_f32 v[78:79], v[78:79], v[192:193] op_sel_hi:[1,0]
	v_pk_mul_f32 v[76:77], v[76:77], v[192:193] op_sel_hi:[1,0]
	v_pk_mul_f32 v[82:83], v[82:83], v[192:193] op_sel:[0,1]
	v_pk_mul_f32 v[80:81], v[80:81], v[192:193] op_sel:[0,1]
	s_waitcnt vmcnt(2)
	v_pk_mul_f32 v[70:71], v[70:71], v[194:195] op_sel_hi:[1,0]
	v_pk_mul_f32 v[68:69], v[68:69], v[194:195] op_sel_hi:[1,0]
	v_pk_mul_f32 v[74:75], v[74:75], v[194:195] op_sel:[0,1]
	v_pk_mul_f32 v[72:73], v[72:73], v[194:195] op_sel:[0,1]
	s_waitcnt vmcnt(1)
	v_pk_mul_f32 v[62:63], v[62:63], v[196:197] op_sel_hi:[1,0]
	v_pk_mul_f32 v[60:61], v[60:61], v[196:197] op_sel_hi:[1,0]
	v_pk_mul_f32 v[66:67], v[66:67], v[196:197] op_sel:[0,1]
	v_pk_mul_f32 v[64:65], v[64:65], v[196:197] op_sel:[0,1]
	s_waitcnt vmcnt(0)
	v_pk_mul_f32 v[54:55], v[54:55], v[198:199] op_sel_hi:[1,0]
	v_pk_mul_f32 v[52:53], v[52:53], v[198:199] op_sel_hi:[1,0]
	v_pk_mul_f32 v[58:59], v[58:59], v[198:199] op_sel:[0,1]
	v_pk_mul_f32 v[56:57], v[56:57], v[198:199] op_sel:[0,1]
	s_branch .LBB0_852
